# speedup vs baseline: 1.0463x; 1.0014x over previous
.LBB0_1009:
	s_mov_b64 s[4:5], 0
	s_add_u32 s24, s86, s4
	s_addc_u32 s25, s87, s5
	v_mov_b32_e32 v51, v1
	s_lshr_b32 s4, s26, 4
	s_lshr_b32 s0, s26, 10
	s_and_b32 s4, s4, 48
	s_and_b32 s27, s26, 15
	v_ashrrev_i32_e32 v12, 3, v51
	s_or_b32 s10, s4, s27
	s_lshl_b64 s[4:5], s[0:1], 13
	v_ashrrev_i32_e32 v13, 31, v12
	s_lshl_b32 s6, s26, 2
	v_lshl_add_u64 v[4:5], s[4:5], 0, v[12:13]
	s_and_b32 s48, s6, 0x3c0
	v_lshlrev_b64 v[4:5], 11, v[4:5]
	s_lshl_b32 s6, s48, 1
	s_mov_b32 s7, s1
	v_lshl_add_u64 v[4:5], s[24:25], 0, v[4:5]
	v_lshlrev_b32_e32 v2, 4, v51
	v_lshl_add_u64 v[4:5], v[4:5], 0, s[6:7]
	v_and_b32_e32 v6, 0x70, v2
	v_mov_b32_e32 v7, v3
	v_lshl_add_u64 v[4:5], v[4:5], 0, v[6:7]
	v_lshl_add_u64 v[36:37], v[4:5], 0, s[16:17]
	v_add_u32_e32 v4, s48, v12
	v_ashrrev_i32_e32 v5, 31, v4
	v_lshlrev_b64 v[4:5], 15, v[4:5]
	v_lshl_add_u64 v[4:5], s[24:25], 0, v[4:5]
	s_lshl_b64 s[8:9], s[0:1], 14
	s_lshl_b32 s0, s10, 1
	v_lshl_add_u64 v[4:5], v[4:5], 0, s[8:9]
	s_or_b32 s28, s0, 1
	v_ashrrev_i32_e32 v13, 6, v51
	v_lshl_add_u64 v[4:5], v[4:5], 0, v[6:7]
	s_lshl_b32 s0, s28, 17
	v_and_b32_e32 v53, 15, v51
	v_lshlrev_b32_e32 v48, 4, v13
	v_lshl_add_u64 v[38:39], v[4:5], 0, s[18:19]
	v_lshl_add_u64 v[4:5], v[36:37], 0, s[0:1]
	s_lshl_b32 s0, s28, 7
	v_or_b32_e32 v54, v48, v53
	s_lshl_b32 s8, s10, 7
	v_lshl_add_u64 v[8:9], v[38:39], 0, s[0:1]
	v_add_u32_e32 v14, s8, v54
	v_mov_b64_e32 v[110:111], v[4:5]
	s_nop 0
	v_mov_b64_e32 v[112:113], v[8:9]
	v_ashrrev_i32_e32 v15, 31, v14
	v_lshl_add_u64 v[14:15], s[4:5], 0, v[14:15]
	v_lshlrev_b64 v[16:17], 11, v[14:15]
	v_lshl_add_u64 v[16:17], s[24:25], 0, v[16:17]
	v_lshl_add_u64 v[16:17], v[16:17], 0, s[6:7]
	v_and_b32_e32 v2, 48, v51
	v_lshl_add_u64 v[16:17], v[16:17], 0, v[2:3]
	v_lshl_add_u64 v[18:19], v[16:17], 0, s[14:15]
	v_add_co_u32_e32 v16, vcc, s40, v16
	s_lshl_b32 s0, s10, 18
	s_nop 0
	v_addc_co_u32_e32 v17, vcc, 0, v17, vcc
	v_mov_b64_e32 v[114:115], v[16:17]
	v_mov_b64_e32 v[116:117], v[18:19]
	v_lshl_add_u64 v[16:17], v[36:37], 0, s[0:1]
	s_lshl_b32 s0, s10, 8
	s_cmp_eq_u32 s55, 0
	s_cbranch_scc1 .Lat_doload
	s_waitcnt vmcnt(4)
	v_mov_b32_e32 v4, v118
	v_mov_b32_e32 v5, v119
	v_mov_b32_e32 v6, v120
	v_mov_b32_e32 v7, v121
	v_mov_b32_e32 v8, v122
	v_mov_b32_e32 v9, v123
	v_mov_b32_e32 v10, v124
	v_mov_b32_e32 v11, v125
	v_mov_b32_e32 v20, v126
	v_mov_b32_e32 v21, v127
	v_mov_b32_e32 v22, v128
	v_mov_b32_e32 v23, v129
	v_mov_b32_e32 v24, v130
	v_mov_b32_e32 v25, v131
	v_mov_b32_e32 v26, v132
	v_mov_b32_e32 v27, v133
	s_branch .Lat_loaded2

.Lat_loaded2:
	v_lshl_add_u64 v[18:19], v[38:39], 0, s[0:1]
	global_load_dwordx4 v[28:31], v[16:17], off
	global_load_dwordx4 v[32:35], v[18:19], off
	v_lshrrev_b32_e32 v17, 1, v51
	v_ashrrev_i32_e32 v18, 5, v51
	v_and_b32_e32 v17, 48, v17
	v_and_b32_e32 v18, -4, v18
	v_and_b32_e32 v19, 3, v12
	v_lshlrev_b32_e32 v40, 7, v12
	v_xor_b32_e32 v12, v12, v51
	v_add_u32_e32 v17, v17, v18
	v_lshlrev_b32_e32 v12, 4, v12
	v_or_b32_e32 v18, v17, v19
	v_bitop3_b32 v17, v17, v51, v19 bitop3:0x36
	v_and_or_b32 v45, v12, s41, v40
	v_lshlrev_b32_e32 v12, 7, v18
	v_lshlrev_b32_e32 v17, 4, v17
	v_and_or_b32 v46, v17, s41, v12
	v_bfe_u32 v44, v51, 4, 2
	v_add_u32_e32 v12, 0, v46
	v_add_u32_e32 v18, 0, v45
	v_and_b32_e32 v16, 63, v51
	s_bfe_u32 s0, s26, 0x20008
	v_sub_u32_e32 v2, v54, v2
	v_lshlrev_b64 v[40:41], 10, v[14:15]
	v_lshl_add_u32 v47, v13, 2, 0
	v_add_u32_e32 v48, s8, v48
	v_cmp_eq_u32_e64 s[8:9], 0, v16
	s_lshl_b32 s50, s0, 11
	s_lshl_b32 s0, s0, 5
	s_lshl_b32 s26, s27, 1
	v_subrev_u32_e32 v54, 64, v2
	ds_write_b128 v12, v[4:7]
	ds_write_b128 v18, v[8:11] offset:8192
	v_xor_b32_e32 v5, 1, v44
	v_cmp_gt_u32_e64 s[10:11], v5, v44
	v_xor_b32_e32 v5, 2, v44
	v_cmp_gt_u32_e64 s[4:5], v5, v44
	v_xor_b32_e32 v5, 3, v44
	v_and_b32_e32 v4, 7, v51
	v_cmp_gt_u32_e64 s[6:7], v5, v44
	v_lshlrev_b32_e32 v5, 1, v44
	v_bitop3_b32 v6, v44, v51, 7 bitop3:0x78
	v_lshlrev_b32_e32 v49, 4, v6
	v_bitop3_b32 v6, v44, v4, 4 bitop3:0x36
	v_bitop3_b32 v4, v5, v4, 1 bitop3:0x36
	v_lshlrev_b32_e32 v50, 4, v6
	v_bitop3_b32 v6, v5, v51, 7 bitop3:0x78
	v_lshlrev_b32_e32 v52, 4, v4
	v_mov_b32_e32 v4, v3
	v_mov_b32_e32 v5, v3
	v_mov_b32_e32 v2, v3
	v_mov_b64_e32 v[10:11], v[4:5]
	v_mov_b64_e32 v[14:15], v[4:5]
	v_mov_b64_e32 v[18:19], v[4:5]
	v_lshlrev_b32_e32 v51, 4, v6
	s_lshl_b32 s49, s27, 7
	s_or_b32 s0, s0, s26
	v_mov_b64_e32 v[8:9], v[2:3]
	v_mov_b64_e32 v[12:13], v[2:3]
	v_mov_b64_e32 v[16:17], v[2:3]
	v_mov_b64_e32 v[6:7], v[4:5]
	v_mov_b32_e32 v56, 0
	v_lshl_add_u32 v53, v53, 7, 0
	s_add_i32 s26, s0, -1
	s_lshl_b32 s53, s28, 3
	s_or_b32 s51, s49, 64
	s_add_i32 s52, s49, 0x80
	v_mov_b32_e32 v55, 1.0
	s_mov_b32 s54, 0
	v_mov_b64_e32 v[4:5], v[2:3]
	s_mov_b32 s55, 0
	s_and_b64 vcc, exec, s[12:13]
	s_cbranch_vccnz .Lat_nopf
	s_cmp_eq_u32 s33, 32
	s_cbranch_scc0 .Lat_nopf
	s_add_i32 s56, s47, 1
	s_mul_i32 s56, s56, s33
	s_add_i32 s56, s56, s38
	s_cmpk_lt_i32 s56, 0x100
	s_cbranch_scc0 .Lat_nopf
	s_mov_b32 s55, 1
	s_mov_b32 s56, 0x400000
	s_mov_b32 s57, 0
	v_lshl_add_u64 v[112:113], v[112:113], 0, s[56:57]
	global_load_dwordx4 v[118:121], v[110:111], off offset:256
	global_load_dwordx4 v[122:125], v[112:113], off
	global_load_dwordx4 v[126:129], v[114:115], off offset:256
	global_load_dwordx4 v[130:133], v[116:117], off offset:320
